# fast path v10: row-sum adds rebalanced across PV gaps + branch-free next-iteration far/near flag in the MFMA shadow
# baseline (speedup 1.0000x reference)
; #define MFMA32(a, b, c) __builtin_amdgcn_mfma_f32_32x32x16_bf16((a), (b), (c), 0, 0, 0)
; DI int crow(int r, int h) { return (r & 3) + 8 * (r >> 2) + 4 * h; }
; DI void attn_item(const Params& p, int g, int seq, int hd, int qt, int m, char* smem, int split_j, int sub) {
;     ...
;   auto compute = [&](int st, int buf) __attribute__((always_inline)) {
;     const int k0 = (tbase + st) * 32, h = h_, l31 = l31_;
;     const bf16_t* Kb = Ks + buf * 32 * 72; const bf16_t* Vb = Vs + buf * 128 * 40;
;     const int rmin = k0 - (qw0 + 31), rmax = k0 + 31 - qw0;
;     const bool farL = rmax <= -128, farR = rmin >= 128;
;     if (!farL && region == 0) { rescale(__builtin_amdgcn_exp2f(cneg)); region = 1; }
;     if (farR && region == 1) { rescale(__builtin_amdgcn_exp2f(-cpos)); region = 2; }
;     bf16x8 kf[4], vf[2][4];
; #pragma unroll
;     for (int s = 0; s < 4; ++s) kf[s] = *(const bf16x8*)(Kb + l31 * 72 + s * 16 + h * 8);
; #pragma unroll
;     for (int s2 = 0; s2 < 2; ++s2)
; #pragma unroll
;       for (int dt = 0; dt < 4; ++dt) vf[s2][dt] = *(const bf16x8*)(Vb + (dt * 32 + l31) * 40 + s2 * 16 + h * 8);
;     __builtin_amdgcn_sched_barrier(0);
;     f32x16 X;
; #pragma unroll
;     for (int r = 0; r < 16; ++r) X[r] = 0.f;
; #pragma unroll
;     for (int s = 0; s < 4; ++s) X = MFMA32(kf[s], qf[s], X);
;     if (farL || farR) {
; #pragma unroll
;       for (int r = 0; r < 16; ++r) X[r] = __builtin_amdgcn_exp2f(X[r]);
;     } else {
;       const int rel0 = k0 - (qw0 + l31) + 128;
; #pragma unroll
;       for (int r = 0; r < 16; ++r) { int idx = rel0 + crow(r, h); idx = idx < 0 ? 0 : (idx > 256 ? 256 : idx); X[r] = __builtin_amdgcn_exp2f(X[r] + tab[idx]); }
;     }
;     bf16x8 pf[2];
; #pragma unroll
;     for (int s2 = 0; s2 < 2; ++s2) {
;       u32x4 w; w.x = pk_bf16(X[8 * s2], X[8 * s2 + 1]); w.y = pk_bf16(X[8 * s2 + 2], X[8 * s2 + 3]); w.z = pk_bf16(X[8 * s2 + 4], X[8 * s2 + 5]); w.w = pk_bf16(X[8 * s2 + 6], X[8 * s2 + 7]);
;       ls2 += (f32x2){X[8 * s2], X[8 * s2 + 1]}; ls2 += (f32x2){X[8 * s2 + 2], X[8 * s2 + 3]};
;       ls2 += (f32x2){X[8 * s2 + 4], X[8 * s2 + 5]}; ls2 += (f32x2){X[8 * s2 + 6], X[8 * s2 + 7]};
;       pf[s2] = __builtin_bit_cast(bf16x8, w);
;     }
; #pragma unroll
;     for (int s2 = 0; s2 < 2; ++s2)
; #pragma unroll
;       for (int dt = 0; dt < 4; ++dt) O[dt] = MFMA32(pf[s2], vf[s2][dt], O[dt]);
.Lat2_reads:
	ds_read_b128 v[64:67], v192
	ds_read_b128 v[80:83], v192 offset:32
	ds_read_b128 v[84:87], v192 offset:64
	ds_read_b128 v[88:91], v192 offset:96
	ds_read_b128 v[220:223], v192 offset:4608
	ds_read_b128 v[224:227], v192 offset:4640
	ds_read_b128 v[236:239], v192 offset:4672
	ds_read_b128 v[240:243], v192 offset:4704
	ds_read_b128 v[156:159], v244 offset:18432
	ds_read_b128 v[160:163], v244 offset:20992
	ds_read_b128 v[164:167], v244 offset:23552
	ds_read_b128 v[152:155], v244 offset:26112
	s_waitcnt lgkmcnt(11)
	v_mfma_f32_32x32x16_bf16 v[64:79], v[64:67], v[104:107], 0
	s_waitcnt lgkmcnt(10)
	v_mfma_f32_32x32x16_bf16 v[64:79], v[80:83], v[108:111], v[64:79]
	s_waitcnt lgkmcnt(9)
	v_mfma_f32_32x32x16_bf16 v[64:79], v[84:87], v[112:115], v[64:79]
	s_waitcnt lgkmcnt(8)
	v_mfma_f32_32x32x16_bf16 v[64:79], v[88:91], v[116:119], v[64:79]
	ds_read_b128 v[148:151], v244 offset:18464
	ds_read_b128 v[144:147], v244 offset:21024
	ds_read_b128 v[136:139], v244 offset:23584
	ds_read_b128 v[140:143], v244 offset:26144
	s_waitcnt lgkmcnt(11)
	v_mfma_f32_32x32x16_bf16 v[80:95], v[220:223], v[104:107], 0
	s_waitcnt lgkmcnt(10)
	v_mfma_f32_32x32x16_bf16 v[80:95], v[224:227], v[108:111], v[80:95]
	v_exp_f32_e32 v64, v64
	v_exp_f32_e32 v65, v65
	v_exp_f32_e32 v66, v66
	v_exp_f32_e32 v67, v67
	v_exp_f32_e32 v68, v68
	v_exp_f32_e32 v69, v69
	s_waitcnt lgkmcnt(9)
	v_mfma_f32_32x32x16_bf16 v[80:95], v[236:239], v[112:115], v[80:95]
	v_exp_f32_e32 v70, v70
	v_exp_f32_e32 v71, v71
	v_exp_f32_e32 v72, v72
	v_exp_f32_e32 v73, v73
	v_exp_f32_e32 v74, v74
	v_exp_f32_e32 v75, v75
	s_waitcnt lgkmcnt(8)
	v_mfma_f32_32x32x16_bf16 v[80:95], v[240:243], v[116:119], v[80:95]
	v_exp_f32_e32 v76, v76
	v_exp_f32_e32 v77, v77
	v_exp_f32_e32 v78, v78
	v_exp_f32_e32 v79, v79
	v_cvt_pk_bf16_f32 v220, v64, v65
	v_cvt_pk_bf16_f32 v221, v66, v67
	v_cvt_pk_bf16_f32 v222, v68, v69
	v_cvt_pk_bf16_f32 v223, v70, v71
	v_cvt_pk_bf16_f32 v224, v72, v73
	v_cvt_pk_bf16_f32 v225, v74, v75
	v_cvt_pk_bf16_f32 v226, v76, v77
	v_cvt_pk_bf16_f32 v227, v78, v79
	s_waitcnt lgkmcnt(7)
	v_mfma_f32_32x32x16_bf16 v[48:63], v[220:223], v[156:159], v[48:63]
	ds_read_b128 v[156:159], v244 offset:28672
	v_exp_f32_e32 v80, v80
	v_exp_f32_e32 v81, v81
	v_exp_f32_e32 v82, v82
	s_waitcnt lgkmcnt(7)
	v_mfma_f32_32x32x16_bf16 v[32:47], v[220:223], v[160:163], v[32:47]
	ds_read_b128 v[160:163], v244 offset:31232
	v_exp_f32_e32 v83, v83
	v_exp_f32_e32 v84, v84
	v_exp_f32_e32 v85, v85
	s_waitcnt lgkmcnt(7)
	v_mfma_f32_32x32x16_bf16 v[16:31], v[220:223], v[164:167], v[16:31]
	ds_read_b128 v[164:167], v244 offset:33792
	v_exp_f32_e32 v86, v86
	v_exp_f32_e32 v87, v87
	v_exp_f32_e32 v88, v88
	s_waitcnt lgkmcnt(7)
	v_mfma_f32_32x32x16_bf16 v[0:15], v[220:223], v[152:155], v[0:15]
	ds_read_b128 v[152:155], v244 offset:36352
	v_exp_f32_e32 v89, v89
	v_exp_f32_e32 v90, v90
	v_exp_f32_e32 v91, v91
	s_waitcnt lgkmcnt(7)
	v_mfma_f32_32x32x16_bf16 v[48:63], v[224:227], v[148:151], v[48:63]
	ds_read_b128 v[148:151], v244 offset:28704
	v_exp_f32_e32 v92, v92
	v_exp_f32_e32 v93, v93
	v_exp_f32_e32 v94, v94
	v_exp_f32_e32 v95, v95
	s_waitcnt lgkmcnt(7)
	v_mfma_f32_32x32x16_bf16 v[32:47], v[224:227], v[144:147], v[32:47]
	ds_read_b128 v[144:147], v244 offset:31264
	v_cvt_pk_bf16_f32 v236, v80, v81
	v_cvt_pk_bf16_f32 v237, v82, v83
	v_cvt_pk_bf16_f32 v238, v84, v85
	v_add_f32_e32 v246, v66, v70
	v_add_f32_e32 v247, v67, v71
	v_add_f32_e32 v186, v186, v64
	v_add_f32_e32 v187, v187, v65
	s_waitcnt lgkmcnt(7)
	v_mfma_f32_32x32x16_bf16 v[16:31], v[224:227], v[136:139], v[16:31]
	ds_read_b128 v[136:139], v244 offset:33824
	v_cvt_pk_bf16_f32 v239, v86, v87
	v_cvt_pk_bf16_f32 v240, v88, v89
	v_cvt_pk_bf16_f32 v241, v90, v91
	v_add_f32_e32 v246, v246, v74
	v_add_f32_e32 v247, v247, v75
	v_add_f32_e32 v186, v186, v68
	v_add_f32_e32 v187, v187, v69
	s_waitcnt lgkmcnt(7)
	v_mfma_f32_32x32x16_bf16 v[0:15], v[224:227], v[140:143], v[0:15]
	ds_read_b128 v[140:143], v244 offset:36384
	v_cvt_pk_bf16_f32 v242, v92, v93
	v_cvt_pk_bf16_f32 v243, v94, v95
	v_add_f32_e32 v246, v246, v78
	v_add_f32_e32 v247, v247, v79
	v_add_f32_e32 v186, v186, v72
	v_add_f32_e32 v187, v187, v73
	s_andn2_b64 vcc, exec, s[8:9]
	s_cbranch_vccnz .Lat2_pvplain
	s_add_i32 s10, s15, 1
	s_cmp_lt_u32 s10, s73
	s_cbranch_scc0 .Lat2_pvw
; DI void attn_item(const Params& p, int g, int seq, int hd, int qt, int m, char* smem, int split_j, int sub) {
;     ...
;   auto compute = [&](int st, int buf) __attribute__((always_inline)) {
;     const int k0 = (tbase + st) * 32, h = h_, l31 = l31_;
;     const bf16_t* Kb = Ks + buf * 32 * 72; const bf16_t* Vb = Vs + buf * 128 * 40;
;     const int rmin = k0 - (qw0 + 31), rmax = k0 + 31 - qw0;
;     const bool farL = rmax <= -128, farR = rmin >= 128;
;     if (!farL && region == 0) { rescale(__builtin_amdgcn_exp2f(cneg)); region = 1; }
;     if (farR && region == 1) { rescale(__builtin_amdgcn_exp2f(-cpos)); region = 2; }
;     bf16x8 kf[4], vf[2][4];
; #pragma unroll
;     for (int s = 0; s < 4; ++s) kf[s] = *(const bf16x8*)(Kb + l31 * 72 + s * 16 + h * 8);
; #pragma unroll
;     for (int s2 = 0; s2 < 2; ++s2)
; #pragma unroll
;       for (int dt = 0; dt < 4; ++dt) vf[s2][dt] = *(const bf16x8*)(Vb + (dt * 32 + l31) * 40 + s2 * 16 + h * 8);
;     __builtin_amdgcn_sched_barrier(0);
;     f32x16 X;
; #pragma unroll
;     for (int r = 0; r < 16; ++r) X[r] = 0.f;
; #pragma unroll
;     for (int s = 0; s < 4; ++s) X = MFMA32(kf[s], qf[s], X);
;     if (farL || farR) {
; #pragma unroll
;       for (int r = 0; r < 16; ++r) X[r] = __builtin_amdgcn_exp2f(X[r]);
;     } else {
;       const int rel0 = k0 - (qw0 + l31) + 128;
; #pragma unroll
;       for (int r = 0; r < 16; ++r) { int idx = rel0 + crow(r, h); idx = idx < 0 ? 0 : (idx > 256 ? 256 : idx); X[r] = __builtin_amdgcn_exp2f(X[r] + tab[idx]); }
;     }
;     bf16x8 pf[2];
; #pragma unroll
;     for (int s2 = 0; s2 < 2; ++s2) {
;       u32x4 w; w.x = pk_bf16(X[8 * s2], X[8 * s2 + 1]); w.y = pk_bf16(X[8 * s2 + 2], X[8 * s2 + 3]); w.z = pk_bf16(X[8 * s2 + 4], X[8 * s2 + 5]); w.w = pk_bf16(X[8 * s2 + 6], X[8 * s2 + 7]);
;       ls2 += (f32x2){X[8 * s2], X[8 * s2 + 1]}; ls2 += (f32x2){X[8 * s2 + 2], X[8 * s2 + 3]};
;       ls2 += (f32x2){X[8 * s2 + 4], X[8 * s2 + 5]}; ls2 += (f32x2){X[8 * s2 + 6], X[8 * s2 + 7]};
;       pf[s2] = __builtin_bit_cast(bf16x8, w);
;     }
; #pragma unroll
;     for (int s2 = 0; s2 < 2; ++s2)
; #pragma unroll
;       for (int dt = 0; dt < 4; ++dt) O[dt] = MFMA32(pf[s2], vf[s2][dt], O[dt]);
;   };
;   load_tile(0, rkA, rvA0, rvA1);
;   load_tile(1, rkB, rvB0, rvB1);
;   __syncthreads();
;   store_tile(0, rkA, rvA0, rvA1);
;   store_tile(1, rkB, rvB0, rvB1);
;   __syncthreads();
	s_xor_b32 s7, s16, 2
	s_mul_i32 s8, s7, 0x2800
	s_add_i32 s8, s8, 32
	s_mulk_i32 s7, 0x1200
	v_add_u32_e32 v192, s7, v169
	v_add3_u32 v244, s8, v189, v190
	s_addk_i32 s8, 0x2800
	s_add_i32 s13, s13, 64
	s_add_i32 s6, s6, 2
	s_mov_b32 s15, s10
	s_mov_b64 s[20:21], 0x1000
	s_waitcnt lgkmcnt(7)
	v_mfma_f32_32x32x16_bf16 v[48:63], v[236:239], v[156:159], v[48:63]
	s_waitcnt vmcnt(5)
	ds_write_b128 v192, v[96:99]
	s_add_i32 s50, s6, -1
	s_lshl_b64 s[10:11], s[50:51], 12
	v_lshl_add_u64 v[220:221], v[172:173], 0, s[10:11]
	v_add_f32_e32 v186, v186, v76
	v_add_f32_e32 v187, v187, v77
	s_waitcnt lgkmcnt(7)
	v_mfma_f32_32x32x16_bf16 v[32:47], v[236:239], v[160:163], v[32:47]
	s_waitcnt vmcnt(4)
	ds_write_b128 v244, v[100:103] offset:18432
	global_load_dwordx4 v[96:99], v[220:221], off
	s_lshl_b64 s[10:11], s[50:51], 13
	v_lshl_add_u64 v[222:223], v[170:171], 0, s[10:11]
	v_add_f32_e32 v186, v186, v246
	v_add_f32_e32 v187, v187, v247
	s_waitcnt lgkmcnt(7)
	v_mfma_f32_32x32x16_bf16 v[16:31], v[236:239], v[164:167], v[16:31]
	s_waitcnt vmcnt(4)
	ds_write_b128 v244, v[120:123] offset:23552
	global_load_dwordx4 v[100:103], v[222:223], off
	v_lshl_add_u64 v[224:225], v[222:223], 0, s[20:21]
	v_add_f32_e32 v246, v82, v86
	v_add_f32_e32 v247, v83, v87
	v_add_f32_e32 v186, v186, v80
	s_waitcnt lgkmcnt(7)
	v_mfma_f32_32x32x16_bf16 v[0:15], v[236:239], v[152:155], v[0:15]
	s_waitcnt vmcnt(4)
	ds_write_b128 v192, v[124:127] offset:4608
	global_load_dwordx4 v[120:123], v[224:225], off
	s_mov_b32 s7, s51
	s_lshl_b64 s[10:11], s[6:7], 12
	v_lshl_add_u64 v[220:221], v[172:173], 0, s[10:11]
	v_add_f32_e32 v187, v187, v81
	v_add_f32_e32 v246, v246, v90
	v_add_f32_e32 v247, v247, v91
	s_waitcnt lgkmcnt(7)
	v_mfma_f32_32x32x16_bf16 v[48:63], v[240:243], v[148:151], v[48:63]
	v_add3_u32 v192, s8, v189, v190
	s_waitcnt vmcnt(4)
	ds_write_b128 v192, v[128:131] offset:18432
	global_load_dwordx4 v[124:127], v[220:221], off
	s_lshl_b64 s[10:11], s[6:7], 13
	v_lshl_add_u64 v[222:223], v[170:171], 0, s[10:11]
	v_add_f32_e32 v186, v186, v84
	v_add_f32_e32 v187, v187, v85
	v_add_f32_e32 v246, v246, v94
	s_waitcnt lgkmcnt(7)
	v_mfma_f32_32x32x16_bf16 v[32:47], v[240:243], v[144:147], v[32:47]
	s_waitcnt vmcnt(4)
	ds_write_b128 v192, v[132:135] offset:23552
	global_load_dwordx4 v[128:131], v[222:223], off
	v_lshl_add_u64 v[224:225], v[222:223], 0, s[20:21]
	v_add_f32_e32 v247, v247, v95
	v_add_f32_e32 v186, v186, v88
	v_add_f32_e32 v187, v187, v89
	s_waitcnt lgkmcnt(7)
	v_mfma_f32_32x32x16_bf16 v[16:31], v[240:243], v[136:139], v[16:31]
	global_load_dwordx4 v[132:135], v[224:225], off
	v_add_f32_e32 v186, v186, v92
	v_add_f32_e32 v187, v187, v93
	s_add_i32 s7, s14, s13
	s_cmpk_lt_i32 s7, 0xff42
	s_cselect_b32 s19, 1, 0
	s_cmpk_gt_i32 s7, 0x9e
	s_cselect_b32 s50, 1, 0
	s_cmp_eq_u32 s17, 2
	s_cselect_b32 s50, s50, 0
	s_or_b32 s19, s19, s50
	s_waitcnt lgkmcnt(6)
	v_mfma_f32_32x32x16_bf16 v[0:15], v[240:243], v[140:143], v[0:15]
	v_add_f32_e32 v186, v186, v246
	v_add_f32_e32 v187, v187, v247
	s_mov_b64 s[8:9], -1
	s_add_i32 s10, s6, -3
	s_and_b32 s16, s10, 2
	s_mul_i32 s10, s16, 0x1200
	s_mul_i32 s18, s16, 0x2800
	v_add_u32_e32 v192, s10, v191
	v_add_u32_e32 v244, s18, v196
	s_cmp_lg_u32 s19, 0
	s_waitcnt lgkmcnt(0)
	s_barrier
	s_cbranch_scc1 .Lat2_reads
	s_branch .LBB0_319
.Lat2_pvw:
	s_xor_b32 s7, s16, 2
	s_mul_i32 s8, s7, 0x2800
	s_add_i32 s8, s8, 32
	s_mulk_i32 s7, 0x1200
	v_add_u32_e32 v192, s7, v169
	v_add3_u32 v244, s8, v189, v190
	s_addk_i32 s8, 0x2800
	s_waitcnt lgkmcnt(7)
	v_mfma_f32_32x32x16_bf16 v[48:63], v[236:239], v[156:159], v[48:63]
	s_waitcnt vmcnt(5)
	ds_write_b128 v192, v[96:99]
	v_add_f32_e32 v186, v186, v76
	v_add_f32_e32 v187, v187, v77
	s_waitcnt lgkmcnt(7)
	v_mfma_f32_32x32x16_bf16 v[32:47], v[236:239], v[160:163], v[32:47]
	s_waitcnt vmcnt(4)
	ds_write_b128 v244, v[100:103] offset:18432
	v_add_f32_e32 v186, v186, v246
	v_add_f32_e32 v187, v187, v247
	s_waitcnt lgkmcnt(7)
	v_mfma_f32_32x32x16_bf16 v[16:31], v[236:239], v[164:167], v[16:31]
	s_waitcnt vmcnt(3)
	ds_write_b128 v244, v[120:123] offset:23552
	v_add_f32_e32 v246, v82, v86
	v_add_f32_e32 v247, v83, v87
	v_add_f32_e32 v186, v186, v80
	s_waitcnt lgkmcnt(7)
	v_mfma_f32_32x32x16_bf16 v[0:15], v[236:239], v[152:155], v[0:15]
	s_waitcnt vmcnt(2)
	ds_write_b128 v192, v[124:127] offset:4608
	v_add_f32_e32 v187, v187, v81
	v_add_f32_e32 v246, v246, v90
	v_add_f32_e32 v247, v247, v91
	s_waitcnt lgkmcnt(7)
	v_mfma_f32_32x32x16_bf16 v[48:63], v[240:243], v[148:151], v[48:63]
	v_add3_u32 v192, s8, v189, v190
	s_waitcnt vmcnt(1)
	ds_write_b128 v192, v[128:131] offset:18432
	v_add_f32_e32 v186, v186, v84
	v_add_f32_e32 v187, v187, v85
	v_add_f32_e32 v246, v246, v94
	s_waitcnt lgkmcnt(7)
	v_mfma_f32_32x32x16_bf16 v[32:47], v[240:243], v[144:147], v[32:47]
	s_waitcnt vmcnt(0)
	ds_write_b128 v192, v[132:135] offset:23552
	v_add_f32_e32 v247, v247, v95
	v_add_f32_e32 v186, v186, v88
	v_add_f32_e32 v187, v187, v89
	s_waitcnt lgkmcnt(7)
	v_mfma_f32_32x32x16_bf16 v[16:31], v[240:243], v[136:139], v[16:31]
	v_add_f32_e32 v186, v186, v92
	v_add_f32_e32 v187, v187, v93
	s_waitcnt lgkmcnt(6)
	v_mfma_f32_32x32x16_bf16 v[0:15], v[240:243], v[140:143], v[0:15]
	v_add_f32_e32 v186, v186, v246
	v_add_f32_e32 v187, v187, v247
	s_branch .Lat2_bot
.Lat2_pvplain:
	s_waitcnt lgkmcnt(7)
	v_mfma_f32_32x32x16_bf16 v[48:63], v[236:239], v[156:159], v[48:63]
	v_add_f32_e32 v186, v186, v76
	v_add_f32_e32 v187, v187, v77
	s_waitcnt lgkmcnt(6)
	v_mfma_f32_32x32x16_bf16 v[32:47], v[236:239], v[160:163], v[32:47]
	v_add_f32_e32 v186, v186, v246
	v_add_f32_e32 v187, v187, v247
	s_waitcnt lgkmcnt(5)
	v_mfma_f32_32x32x16_bf16 v[16:31], v[236:239], v[164:167], v[16:31]
	v_add_f32_e32 v246, v82, v86
	v_add_f32_e32 v247, v83, v87
	v_add_f32_e32 v186, v186, v80
	s_waitcnt lgkmcnt(4)
	v_mfma_f32_32x32x16_bf16 v[0:15], v[236:239], v[152:155], v[0:15]
	v_add_f32_e32 v187, v187, v81
	v_add_f32_e32 v246, v246, v90
	v_add_f32_e32 v247, v247, v91
	s_waitcnt lgkmcnt(3)
	v_mfma_f32_32x32x16_bf16 v[48:63], v[240:243], v[148:151], v[48:63]
	v_add_f32_e32 v186, v186, v84
	v_add_f32_e32 v187, v187, v85
	v_add_f32_e32 v246, v246, v94
	s_waitcnt lgkmcnt(2)
	v_mfma_f32_32x32x16_bf16 v[32:47], v[240:243], v[144:147], v[32:47]
	v_add_f32_e32 v247, v247, v95
	v_add_f32_e32 v186, v186, v88
	v_add_f32_e32 v187, v187, v89
	s_waitcnt lgkmcnt(1)
	v_mfma_f32_32x32x16_bf16 v[16:31], v[240:243], v[136:139], v[16:31]
	v_add_f32_e32 v186, v186, v92
	v_add_f32_e32 v187, v187, v93
	s_waitcnt lgkmcnt(0)
	v_mfma_f32_32x32x16_bf16 v[0:15], v[240:243], v[140:143], v[0:15]
	v_add_f32_e32 v186, v186, v246
	v_add_f32_e32 v187, v187, v247
